# v19 plus NA attention output stored as 16-byte pieces after a permlane32 exchange between the two lanes of a row (was 8-byte pieces)
# speedup vs baseline: 1.0009x; 1.0009x over previous
.LBB0_243:
	s_or_b64 exec, exec, s[2:3]
	v_mov_b32_e32 v32, v117
	s_nop 1
	v_permlane32_swap_b32_e32 v117, v32
	v_add_f32_e32 v32, v117, v32
	v_div_scale_f32 v33, s[0:1], v32, v32, 1.0
	v_rcp_f32_e32 v34, v33
	v_mov_b32_e32 v83, v65
	v_mov_b32_e32 v77, v65
	v_add_u32_e32 v69, s84, v69
	v_fma_f32 v35, -v33, v34, 1.0
	v_fmac_f32_e32 v34, v35, v34
	v_div_scale_f32 v35, vcc, 1.0, v32, 1.0
	v_mul_f32_e32 v36, v35, v34
	v_fma_f32 v37, -v33, v36, v35
	v_fmac_f32_e32 v36, v37, v34
	v_fma_f32 v33, -v33, v36, v35
	v_div_fmas_f32 v33, v33, v34, v36
	v_lshlrev_b64 v[34:35], 11, v[80:81]
	v_div_fixup_f32 v32, v33, v32, 1.0
	v_lshl_add_u64 v[34:35], s[20:21], 0, v[34:35]
	v_lshl_add_u64 v[34:35], v[34:35], 0, v[82:83]
	v_pk_mul_f32 v[0:1], v[0:1], v[32:33] op_sel_hi:[1,0]
	v_pk_mul_f32 v[2:3], v[2:3], v[32:33] op_sel_hi:[1,0]
	v_cvt_pk_bf16_f32 v162, v0, v1
	v_cvt_pk_bf16_f32 v163, v2, v3
	v_pk_mul_f32 v[4:5], v[4:5], v[32:33] op_sel_hi:[1,0]
	v_pk_mul_f32 v[6:7], v[6:7], v[32:33] op_sel_hi:[1,0]
	v_cvt_pk_bf16_f32 v164, v4, v5
	v_cvt_pk_bf16_f32 v165, v6, v7
	v_pk_mul_f32 v[8:9], v[8:9], v[32:33] op_sel_hi:[1,0]
	v_pk_mul_f32 v[10:11], v[10:11], v[32:33] op_sel_hi:[1,0]
	v_cvt_pk_bf16_f32 v166, v8, v9
	v_cvt_pk_bf16_f32 v167, v10, v11
	v_pk_mul_f32 v[12:13], v[12:13], v[32:33] op_sel_hi:[1,0]
	v_pk_mul_f32 v[14:15], v[14:15], v[32:33] op_sel_hi:[1,0]
	v_cvt_pk_bf16_f32 v168, v12, v13
	v_cvt_pk_bf16_f32 v169, v14, v15
	v_pk_mul_f32 v[16:17], v[16:17], v[32:33] op_sel_hi:[1,0]
	v_pk_mul_f32 v[18:19], v[18:19], v[32:33] op_sel_hi:[1,0]
	v_cvt_pk_bf16_f32 v170, v16, v17
	v_cvt_pk_bf16_f32 v171, v18, v19
	v_pk_mul_f32 v[20:21], v[20:21], v[32:33] op_sel_hi:[1,0]
	v_pk_mul_f32 v[22:23], v[22:23], v[32:33] op_sel_hi:[1,0]
	v_cvt_pk_bf16_f32 v172, v20, v21
	v_cvt_pk_bf16_f32 v173, v22, v23
	v_pk_mul_f32 v[24:25], v[24:25], v[32:33] op_sel_hi:[1,0]
	v_pk_mul_f32 v[26:27], v[26:27], v[32:33] op_sel_hi:[1,0]
	v_cvt_pk_bf16_f32 v174, v24, v25
	v_cvt_pk_bf16_f32 v175, v26, v27
	v_pk_mul_f32 v[28:29], v[28:29], v[32:33] op_sel_hi:[1,0]
	v_pk_mul_f32 v[30:31], v[30:31], v[32:33] op_sel_hi:[1,0]
	v_cvt_pk_bf16_f32 v176, v28, v29
	v_cvt_pk_bf16_f32 v177, v30, v31
	s_nop 1
	v_permlane32_swap_b32_e32 v162, v164
	v_permlane32_swap_b32_e32 v163, v165
	v_permlane32_swap_b32_e32 v166, v168
	v_permlane32_swap_b32_e32 v167, v169
	v_permlane32_swap_b32_e32 v170, v172
	v_permlane32_swap_b32_e32 v171, v173
	v_permlane32_swap_b32_e32 v174, v176
	v_permlane32_swap_b32_e32 v175, v177
	v_lshl_add_u64 v[2:3], v[76:77], 1, v[34:35]
	global_store_dwordx4 v[2:3], v[162:165], off
	global_store_dwordx4 v[2:3], v[166:169], off offset:32
	global_store_dwordx4 v[2:3], v[170:173], off offset:64
	global_store_dwordx4 v[2:3], v[174:177], off offset:96
	s_movk_i32 s0, 0xfff
	v_cmp_lt_i32_e32 vcc, s0, v69
	s_or_b64 s[16:17], vcc, s[16:17]
	s_andn2_b64 exec, exec, s[16:17]
	s_cbranch_execz .LBB0_250

.LBB0_828:
	s_or_b64 exec, exec, s[2:3]
	v_mov_b32_e32 v32, v130
	s_nop 1
	v_permlane32_swap_b32_e32 v130, v32
	v_add_f32_e32 v32, v130, v32
	v_div_scale_f32 v33, s[0:1], v32, v32, 1.0
	v_rcp_f32_e32 v34, v33
	v_mov_b32_e32 v97, v65
	v_mov_b32_e32 v91, v65
	v_add_u32_e32 v69, s84, v69
	v_fma_f32 v35, -v33, v34, 1.0
	v_fmac_f32_e32 v34, v35, v34
	v_div_scale_f32 v35, vcc, 1.0, v32, 1.0
	v_mul_f32_e32 v36, v35, v34
	v_fma_f32 v37, -v33, v36, v35
	v_fmac_f32_e32 v36, v37, v34
	v_fma_f32 v33, -v33, v36, v35
	v_div_fmas_f32 v33, v33, v34, v36
	v_lshlrev_b64 v[34:35], 11, v[94:95]
	v_div_fixup_f32 v32, v33, v32, 1.0
	v_lshl_add_u64 v[34:35], s[18:19], 0, v[34:35]
	v_lshl_add_u64 v[34:35], v[34:35], 0, v[96:97]
	v_pk_mul_f32 v[0:1], v[0:1], v[32:33] op_sel_hi:[1,0]
	v_pk_mul_f32 v[2:3], v[2:3], v[32:33] op_sel_hi:[1,0]
	v_cvt_pk_bf16_f32 v162, v0, v1
	v_cvt_pk_bf16_f32 v163, v2, v3
	v_pk_mul_f32 v[4:5], v[4:5], v[32:33] op_sel_hi:[1,0]
	v_pk_mul_f32 v[6:7], v[6:7], v[32:33] op_sel_hi:[1,0]
	v_cvt_pk_bf16_f32 v164, v4, v5
	v_cvt_pk_bf16_f32 v165, v6, v7
	v_pk_mul_f32 v[8:9], v[8:9], v[32:33] op_sel_hi:[1,0]
	v_pk_mul_f32 v[10:11], v[10:11], v[32:33] op_sel_hi:[1,0]
	v_cvt_pk_bf16_f32 v166, v8, v9
	v_cvt_pk_bf16_f32 v167, v10, v11
	v_pk_mul_f32 v[12:13], v[12:13], v[32:33] op_sel_hi:[1,0]
	v_pk_mul_f32 v[14:15], v[14:15], v[32:33] op_sel_hi:[1,0]
	v_cvt_pk_bf16_f32 v168, v12, v13
	v_cvt_pk_bf16_f32 v169, v14, v15
	v_pk_mul_f32 v[16:17], v[16:17], v[32:33] op_sel_hi:[1,0]
	v_pk_mul_f32 v[18:19], v[18:19], v[32:33] op_sel_hi:[1,0]
	v_cvt_pk_bf16_f32 v170, v16, v17
	v_cvt_pk_bf16_f32 v171, v18, v19
	v_pk_mul_f32 v[20:21], v[20:21], v[32:33] op_sel_hi:[1,0]
	v_pk_mul_f32 v[22:23], v[22:23], v[32:33] op_sel_hi:[1,0]
	v_cvt_pk_bf16_f32 v172, v20, v21
	v_cvt_pk_bf16_f32 v173, v22, v23
	v_pk_mul_f32 v[24:25], v[24:25], v[32:33] op_sel_hi:[1,0]
	v_pk_mul_f32 v[26:27], v[26:27], v[32:33] op_sel_hi:[1,0]
	v_cvt_pk_bf16_f32 v174, v24, v25
	v_cvt_pk_bf16_f32 v175, v26, v27
	v_pk_mul_f32 v[28:29], v[28:29], v[32:33] op_sel_hi:[1,0]
	v_pk_mul_f32 v[30:31], v[30:31], v[32:33] op_sel_hi:[1,0]
	v_cvt_pk_bf16_f32 v176, v28, v29
	v_cvt_pk_bf16_f32 v177, v30, v31
	s_nop 1
	v_permlane32_swap_b32_e32 v162, v164
	v_permlane32_swap_b32_e32 v163, v165
	v_permlane32_swap_b32_e32 v166, v168
	v_permlane32_swap_b32_e32 v167, v169
	v_permlane32_swap_b32_e32 v170, v172
	v_permlane32_swap_b32_e32 v171, v173
	v_permlane32_swap_b32_e32 v174, v176
	v_permlane32_swap_b32_e32 v175, v177
	v_lshl_add_u64 v[2:3], v[90:91], 1, v[34:35]
	global_store_dwordx4 v[2:3], v[162:165], off
	global_store_dwordx4 v[2:3], v[166:169], off offset:32
	global_store_dwordx4 v[2:3], v[170:173], off offset:64
	global_store_dwordx4 v[2:3], v[174:177], off offset:96
	s_movk_i32 s0, 0xfff
	v_cmp_lt_i32_e32 vcc, s0, v69
	s_or_b64 s[16:17], vcc, s[16:17]
	s_andn2_b64 exec, exec, s[16:17]
	s_cbranch_execz .LBB0_835
